# grid-barrier spin loops poll 6x less often (s_sleep 6) to take polling traffic off the L2 while stragglers finish
# speedup vs baseline: 1.0043x; 1.0043x over previous
.LBB0_16:
	s_sleep 6
	global_load_dword v2, v0, s[6:7] offset:32 sc1
	s_waitcnt vmcnt(0)
	v_and_b32_e32 v2, 0xffff0000, v2
	v_cmp_ne_u32_e32 vcc, v2, v1
	s_or_b64 s[8:9], vcc, s[8:9]
	s_andn2_b64 exec, exec, s[8:9]
	s_cbranch_execnz .LBB0_16

.LBB0_83:
	global_load_dword v15, v16, s[58:59] offset:1024 sc1
	global_load_dword v0, v16, s[58:59] offset:1280 sc1
	global_load_dword v1, v16, s[58:59] offset:1536 sc1
	global_load_dword v2, v16, s[58:59] offset:1792 sc1
	global_load_dword v3, v16, s[58:59] offset:2048 sc1
	global_load_dword v4, v16, s[58:59] offset:2304 sc1
	global_load_dword v5, v16, s[58:59] offset:2560 sc1
	global_load_dword v6, v16, s[58:59] offset:2816 sc1
	global_load_dword v7, v16, s[58:59] offset:3072 sc1
	global_load_dword v8, v16, s[58:59] offset:3328 sc1
	global_load_dword v9, v16, s[58:59] offset:3584 sc1
	global_load_dword v10, v16, s[58:59] offset:3840 sc1
	global_load_dword v11, v16, s[6:7] sc1
	global_load_dword v12, v16, s[8:9] sc1
	global_load_dword v13, v16, s[10:11] sc1
	global_load_dword v14, v16, s[12:13] sc1
	s_mov_b64 s[14:15], -1
	s_mov_b64 s[18:19], -1
	s_waitcnt vmcnt(14)
	v_add_u32_e32 v17, v0, v15
	s_waitcnt vmcnt(13)
	v_add_u32_e32 v17, v17, v1
	s_waitcnt vmcnt(12)
	v_add_u32_e32 v17, v17, v2
	s_waitcnt vmcnt(11)
	v_add_u32_e32 v17, v17, v3
	s_waitcnt vmcnt(10)
	v_add_u32_e32 v17, v17, v4
	s_waitcnt vmcnt(9)
	v_add_u32_e32 v17, v17, v5
	s_waitcnt vmcnt(8)
	v_add_u32_e32 v17, v17, v6
	s_waitcnt vmcnt(7)
	v_add_u32_e32 v17, v17, v7
	s_waitcnt vmcnt(6)
	v_add_u32_e32 v17, v17, v8
	s_waitcnt vmcnt(5)
	v_add_u32_e32 v17, v17, v9
	s_waitcnt vmcnt(4)
	v_add_u32_e32 v17, v17, v10
	s_waitcnt vmcnt(3)
	v_add_u32_e32 v17, v17, v11
	s_waitcnt vmcnt(2)
	v_add_u32_e32 v17, v17, v12
	s_waitcnt vmcnt(1)
	v_add_u32_e32 v17, v17, v13
	s_waitcnt vmcnt(0)
	v_add_u32_e32 v17, v17, v14
	v_cmp_eq_u32_e32 vcc, s3, v17
	s_cbranch_vccnz .LBB0_82
	s_and_b32 s14, s16, 0xff
	s_cmp_eq_u32 s14, 0
	s_mov_b64 s[14:15], -1
	s_mov_b64 s[20:21], -1
	s_sleep 6
	s_cbranch_scc1 .LBB0_87
	s_and_b64 vcc, exec, s[20:21]
	s_cbranch_vccz .LBB0_82

.LBB0_97:
	s_and_b32 s16, s3, 0xff
	s_mov_b64 s[20:21], -1
	s_cmp_lg_u32 s16, 0
	s_mov_b64 s[26:27], -1
	s_sleep 6
	s_cbranch_scc0 .LBB0_100
	s_and_b64 vcc, exec, s[26:27]
	s_cbranch_vccz .LBB0_96

.LBB0_111:
	s_and_b32 s16, s3, 0xff
	s_cmp_lg_u32 s16, 0
	s_mov_b64 s[26:27], -1
	s_sleep 6
	s_cbranch_scc0 .LBB0_114
	s_mov_b64 s[34:35], -1
	s_and_b64 vcc, exec, s[26:27]
	s_cbranch_vccz .LBB0_110

.LBB0_141:
	global_load_dword v15, v16, s[58:59] offset:1024 sc1
	global_load_dword v0, v16, s[58:59] offset:1280 sc1
	global_load_dword v1, v16, s[58:59] offset:1536 sc1
	global_load_dword v2, v16, s[58:59] offset:1792 sc1
	global_load_dword v3, v16, s[58:59] offset:2048 sc1
	global_load_dword v4, v16, s[58:59] offset:2304 sc1
	global_load_dword v5, v16, s[58:59] offset:2560 sc1
	global_load_dword v6, v16, s[58:59] offset:2816 sc1
	global_load_dword v7, v16, s[58:59] offset:3072 sc1
	global_load_dword v8, v16, s[58:59] offset:3328 sc1
	global_load_dword v9, v16, s[58:59] offset:3584 sc1
	global_load_dword v10, v16, s[58:59] offset:3840 sc1
	global_load_dword v11, v16, s[4:5] sc1
	global_load_dword v12, v16, s[8:9] sc1
	global_load_dword v13, v16, s[10:11] sc1
	global_load_dword v14, v16, s[12:13] sc1
	s_mov_b64 s[14:15], -1
	s_mov_b64 s[18:19], -1
	s_waitcnt vmcnt(14)
	v_add_u32_e32 v17, v0, v15
	s_waitcnt vmcnt(13)
	v_add_u32_e32 v17, v17, v1
	s_waitcnt vmcnt(12)
	v_add_u32_e32 v17, v17, v2
	s_waitcnt vmcnt(11)
	v_add_u32_e32 v17, v17, v3
	s_waitcnt vmcnt(10)
	v_add_u32_e32 v17, v17, v4
	s_waitcnt vmcnt(9)
	v_add_u32_e32 v17, v17, v5
	s_waitcnt vmcnt(8)
	v_add_u32_e32 v17, v17, v6
	s_waitcnt vmcnt(7)
	v_add_u32_e32 v17, v17, v7
	s_waitcnt vmcnt(6)
	v_add_u32_e32 v17, v17, v8
	s_waitcnt vmcnt(5)
	v_add_u32_e32 v17, v17, v9
	s_waitcnt vmcnt(4)
	v_add_u32_e32 v17, v17, v10
	s_waitcnt vmcnt(3)
	v_add_u32_e32 v17, v17, v11
	s_waitcnt vmcnt(2)
	v_add_u32_e32 v17, v17, v12
	s_waitcnt vmcnt(1)
	v_add_u32_e32 v17, v17, v13
	s_waitcnt vmcnt(0)
	v_add_u32_e32 v17, v17, v14
	v_cmp_eq_u32_e32 vcc, s3, v17
	s_cbranch_vccnz .LBB0_140
	s_and_b32 s14, s16, 0xff
	s_cmp_eq_u32 s14, 0
	s_mov_b64 s[14:15], -1
	s_mov_b64 s[20:21], -1
	s_sleep 6
	s_cbranch_scc1 .LBB0_145
	s_and_b64 vcc, exec, s[20:21]
	s_cbranch_vccz .LBB0_140

.LBB0_392:
	global_load_dword v15, v16, s[58:59] offset:1024 sc1
	global_load_dword v0, v16, s[58:59] offset:1280 sc1
	global_load_dword v1, v16, s[58:59] offset:1536 sc1
	global_load_dword v2, v16, s[58:59] offset:1792 sc1
	global_load_dword v3, v16, s[58:59] offset:2048 sc1
	global_load_dword v4, v16, s[58:59] offset:2304 sc1
	global_load_dword v5, v16, s[58:59] offset:2560 sc1
	global_load_dword v6, v16, s[58:59] offset:2816 sc1
	global_load_dword v7, v16, s[58:59] offset:3072 sc1
	global_load_dword v8, v16, s[58:59] offset:3328 sc1
	global_load_dword v9, v16, s[58:59] offset:3584 sc1
	global_load_dword v10, v16, s[58:59] offset:3840 sc1
	global_load_dword v11, v16, s[6:7] sc1
	global_load_dword v12, v16, s[8:9] sc1
	global_load_dword v13, v16, s[10:11] sc1
	global_load_dword v14, v16, s[12:13] sc1
	s_mov_b64 s[14:15], -1
	s_mov_b64 s[16:17], -1
	s_waitcnt vmcnt(14)
	v_add_u32_e32 v17, v0, v15
	s_waitcnt vmcnt(13)
	v_add_u32_e32 v17, v17, v1
	s_waitcnt vmcnt(12)
	v_add_u32_e32 v17, v17, v2
	s_waitcnt vmcnt(11)
	v_add_u32_e32 v17, v17, v3
	s_waitcnt vmcnt(10)
	v_add_u32_e32 v17, v17, v4
	s_waitcnt vmcnt(9)
	v_add_u32_e32 v17, v17, v5
	s_waitcnt vmcnt(8)
	v_add_u32_e32 v17, v17, v6
	s_waitcnt vmcnt(7)
	v_add_u32_e32 v17, v17, v7
	s_waitcnt vmcnt(6)
	v_add_u32_e32 v17, v17, v8
	s_waitcnt vmcnt(5)
	v_add_u32_e32 v17, v17, v9
	s_waitcnt vmcnt(4)
	v_add_u32_e32 v17, v17, v10
	s_waitcnt vmcnt(3)
	v_add_u32_e32 v17, v17, v11
	s_waitcnt vmcnt(2)
	v_add_u32_e32 v17, v17, v12
	s_waitcnt vmcnt(1)
	v_add_u32_e32 v17, v17, v13
	s_waitcnt vmcnt(0)
	v_add_u32_e32 v17, v17, v14
	v_cmp_eq_u32_e32 vcc, s3, v17
	s_cbranch_vccnz .LBB0_391
	s_and_b32 s14, s20, 0xff
	s_cmp_eq_u32 s14, 0
	s_mov_b64 s[14:15], -1
	s_mov_b64 s[18:19], -1
	s_sleep 6
	s_cbranch_scc1 .LBB0_396
	s_and_b64 vcc, exec, s[18:19]
	s_cbranch_vccz .LBB0_391

.LBB0_406:
	s_and_b32 s20, s3, 0xff
	s_mov_b64 s[18:19], -1
	s_cmp_lg_u32 s20, 0
	s_mov_b64 s[24:25], -1
	s_sleep 6
	s_cbranch_scc0 .LBB0_409
	s_and_b64 vcc, exec, s[24:25]
	s_cbranch_vccz .LBB0_405

.LBB0_420:
	s_and_b32 s20, s3, 0xff
	s_cmp_lg_u32 s20, 0
	s_mov_b64 s[24:25], -1
	s_sleep 6
	s_cbranch_scc0 .LBB0_423
	s_mov_b64 s[26:27], -1
	s_and_b64 vcc, exec, s[24:25]
	s_cbranch_vccz .LBB0_419

.LBB0_663:
	global_load_dword v15, v16, s[58:59] offset:1024 sc1
	global_load_dword v0, v16, s[58:59] offset:1280 sc1
	global_load_dword v1, v16, s[58:59] offset:1536 sc1
	global_load_dword v2, v16, s[58:59] offset:1792 sc1
	global_load_dword v3, v16, s[58:59] offset:2048 sc1
	global_load_dword v4, v16, s[58:59] offset:2304 sc1
	global_load_dword v5, v16, s[58:59] offset:2560 sc1
	global_load_dword v6, v16, s[58:59] offset:2816 sc1
	global_load_dword v7, v16, s[58:59] offset:3072 sc1
	global_load_dword v8, v16, s[58:59] offset:3328 sc1
	global_load_dword v9, v16, s[58:59] offset:3584 sc1
	global_load_dword v10, v16, s[58:59] offset:3840 sc1
	global_load_dword v11, v16, s[4:5] sc1
	global_load_dword v12, v16, s[8:9] sc1
	global_load_dword v13, v16, s[10:11] sc1
	global_load_dword v14, v16, s[12:13] sc1
	s_mov_b64 s[14:15], -1
	s_mov_b64 s[16:17], -1
	s_waitcnt vmcnt(14)
	v_add_u32_e32 v17, v0, v15
	s_waitcnt vmcnt(13)
	v_add_u32_e32 v17, v17, v1
	s_waitcnt vmcnt(12)
	v_add_u32_e32 v17, v17, v2
	s_waitcnt vmcnt(11)
	v_add_u32_e32 v17, v17, v3
	s_waitcnt vmcnt(10)
	v_add_u32_e32 v17, v17, v4
	s_waitcnt vmcnt(9)
	v_add_u32_e32 v17, v17, v5
	s_waitcnt vmcnt(8)
	v_add_u32_e32 v17, v17, v6
	s_waitcnt vmcnt(7)
	v_add_u32_e32 v17, v17, v7
	s_waitcnt vmcnt(6)
	v_add_u32_e32 v17, v17, v8
	s_waitcnt vmcnt(5)
	v_add_u32_e32 v17, v17, v9
	s_waitcnt vmcnt(4)
	v_add_u32_e32 v17, v17, v10
	s_waitcnt vmcnt(3)
	v_add_u32_e32 v17, v17, v11
	s_waitcnt vmcnt(2)
	v_add_u32_e32 v17, v17, v12
	s_waitcnt vmcnt(1)
	v_add_u32_e32 v17, v17, v13
	s_waitcnt vmcnt(0)
	v_add_u32_e32 v17, v17, v14
	v_cmp_eq_u32_e32 vcc, s3, v17
	s_cbranch_vccnz .LBB0_662
	s_and_b32 s14, s20, 0xff
	s_cmp_eq_u32 s14, 0
	s_mov_b64 s[14:15], -1
	s_mov_b64 s[18:19], -1
	s_sleep 6
	s_cbranch_scc1 .LBB0_667
	s_and_b64 vcc, exec, s[18:19]
	s_cbranch_vccz .LBB0_662

.LBB0_757:
	s_and_b32 s20, s3, 0xff
	s_mov_b64 s[18:19], -1
	s_cmp_lg_u32 s20, 0
	s_mov_b64 s[22:23], -1
	s_sleep 6
	s_cbranch_scc0 .LBB0_760
	s_and_b64 vcc, exec, s[22:23]
	s_cbranch_vccz .LBB0_756

.LBB0_771:
	s_and_b32 s20, s3, 0xff
	s_cmp_lg_u32 s20, 0
	s_mov_b64 s[22:23], -1
	s_sleep 6
	s_cbranch_scc0 .LBB0_774
	s_mov_b64 s[24:25], -1
	s_and_b64 vcc, exec, s[22:23]
	s_cbranch_vccz .LBB0_770

.LBB0_935:
	global_load_dword v15, v16, s[58:59] offset:1024 sc1
	global_load_dword v0, v16, s[58:59] offset:1280 sc1
	global_load_dword v1, v16, s[58:59] offset:1536 sc1
	global_load_dword v2, v16, s[58:59] offset:1792 sc1
	global_load_dword v3, v16, s[58:59] offset:2048 sc1
	global_load_dword v4, v16, s[58:59] offset:2304 sc1
	global_load_dword v5, v16, s[58:59] offset:2560 sc1
	global_load_dword v6, v16, s[58:59] offset:2816 sc1
	global_load_dword v7, v16, s[58:59] offset:3072 sc1
	global_load_dword v8, v16, s[58:59] offset:3328 sc1
	global_load_dword v9, v16, s[58:59] offset:3584 sc1
	global_load_dword v10, v16, s[58:59] offset:3840 sc1
	global_load_dword v11, v16, s[0:1] sc1
	global_load_dword v12, v16, s[4:5] sc1
	global_load_dword v13, v16, s[6:7] sc1
	global_load_dword v14, v16, s[8:9] sc1
	s_mov_b64 s[10:11], -1
	s_mov_b64 s[12:13], -1
	s_waitcnt vmcnt(14)
	v_add_u32_e32 v17, v0, v15
	s_waitcnt vmcnt(13)
	v_add_u32_e32 v17, v17, v1
	s_waitcnt vmcnt(12)
	v_add_u32_e32 v17, v17, v2
	s_waitcnt vmcnt(11)
	v_add_u32_e32 v17, v17, v3
	s_waitcnt vmcnt(10)
	v_add_u32_e32 v17, v17, v4
	s_waitcnt vmcnt(9)
	v_add_u32_e32 v17, v17, v5
	s_waitcnt vmcnt(8)
	v_add_u32_e32 v17, v17, v6
	s_waitcnt vmcnt(7)
	v_add_u32_e32 v17, v17, v7
	s_waitcnt vmcnt(6)
	v_add_u32_e32 v17, v17, v8
	s_waitcnt vmcnt(5)
	v_add_u32_e32 v17, v17, v9
	s_waitcnt vmcnt(4)
	v_add_u32_e32 v17, v17, v10
	s_waitcnt vmcnt(3)
	v_add_u32_e32 v17, v17, v11
	s_waitcnt vmcnt(2)
	v_add_u32_e32 v17, v17, v12
	s_waitcnt vmcnt(1)
	v_add_u32_e32 v17, v17, v13
	s_waitcnt vmcnt(0)
	v_add_u32_e32 v17, v17, v14
	v_cmp_eq_u32_e32 vcc, s16, v17
	s_cbranch_vccnz .LBB0_934
	s_and_b32 s10, s17, 0xff
	s_cmp_eq_u32 s10, 0
	s_mov_b64 s[10:11], -1
	s_mov_b64 s[14:15], -1
	s_sleep 6
	s_cbranch_scc1 .LBB0_939
	s_and_b64 vcc, exec, s[14:15]
	s_cbranch_vccz .LBB0_934

.LBB0_949:
	s_and_b32 s16, s20, 0xff
	s_mov_b64 s[14:15], -1
	s_cmp_lg_u32 s16, 0
	s_mov_b64 s[18:19], -1
	s_sleep 6
	s_cbranch_scc0 .LBB0_952
	s_and_b64 vcc, exec, s[18:19]
	s_cbranch_vccz .LBB0_948

.LBB0_963:
	s_and_b32 s16, s22, 0xff
	s_cmp_lg_u32 s16, 0
	s_mov_b64 s[18:19], -1
	s_sleep 6
	s_cbranch_scc0 .LBB0_966
	s_mov_b64 s[20:21], -1
	s_and_b64 vcc, exec, s[18:19]
	s_cbranch_vccz .LBB0_962
